# M13 + cvt_tile (P0 weight conversion): all 8 W rows and ks values of a tile loaded up front
# baseline (speedup 1.0000x reference)
.LBB0_87:
	s_andn2_b64 vcc, exec, s[38:39]
	s_cbranch_vccnz .LBB0_64
	s_ashr_i32 s83, s82, 31
	s_lshl_b64 s[88:89], s[82:83], 2
	s_add_u32 s40, s40, s88
	s_addc_u32 s41, s41, s89
	v_lshlrev_b32_e32 v114, 2, v8
	v_add_u32_e32 v2, s82, v8
	v_lshl_add_u64 v[14:15], s[40:41], 0, v[114:115]
	v_mov_b32_e32 v114, v115
	v_cmp_gt_i32_e64 s[38:39], s4, v2
	v_mov_b32_e32 v116, v115
	v_mov_b32_e32 v117, v115
	v_add_u32_e32 v16, s80, v37
	v_mov_b64_e32 v[2:3], v[114:115]
	v_ashrrev_i32_e32 v17, 31, v16
	v_mov_b64_e32 v[4:5], v[116:117]
	v_mov_b32_e32 v68, v115
	v_mov_b32_e32 v69, v115
	v_mov_b32_e32 v70, v115
	v_mov_b32_e32 v71, v115
	v_mov_b32_e32 v72, v115
	v_mov_b32_e32 v73, v115
	v_mov_b32_e32 v74, v115
	v_mov_b32_e32 v75, v115
	v_mov_b32_e32 v76, v115
	v_mov_b32_e32 v77, v115
	v_mov_b32_e32 v78, v115
	v_mov_b32_e32 v79, v115
	v_mov_b32_e32 v80, v115
	v_mov_b32_e32 v81, v115
	v_mov_b32_e32 v82, v115
	v_mov_b32_e32 v83, v115
	v_mov_b32_e32 v84, v115
	v_mov_b32_e32 v85, v115
	v_mov_b32_e32 v86, v115
	v_mov_b32_e32 v87, v115
	v_mov_b32_e32 v88, v115
	v_mov_b32_e32 v89, v115
	v_mov_b32_e32 v90, v115
	v_mov_b32_e32 v91, v115
	v_mov_b32_e32 v92, v115
	v_mov_b32_e32 v93, v115
	v_mov_b32_e32 v94, v115
	v_mov_b32_e32 v95, v115
	v_mov_b32_e32 v96, v115
	v_mov_b32_e32 v97, v115
	v_mov_b32_e32 v98, v115
	v_mov_b32_e32 v99, v115
	s_and_saveexec_b64 s[40:41], s[38:39]
	s_cbranch_execz .Lcvt_skipA
	v_add_u32_e32 v120, s80, v37
	v_ashrrev_i32_e32 v121, 31, v120
	v_mad_u64_u32 v[122:123], s[88:89], v120, s4, 0
	v_mov_b32_e32 v124, v123
	v_mov_b32_e32 v125, v115
	v_mad_u64_u32 v[124:125], s[88:89], v121, s4, v[124:125]
	v_mov_b32_e32 v123, v124
	v_lshl_add_u64 v[122:123], v[122:123], 2, v[14:15]
	global_load_dwordx4 v[68:71], v[122:123], off nt
	v_add_u32_e32 v120, s80, v7
	v_ashrrev_i32_e32 v121, 31, v120
	v_mad_u64_u32 v[122:123], s[88:89], v120, s4, 0
	v_mov_b32_e32 v124, v123
	v_mov_b32_e32 v125, v115
	v_mad_u64_u32 v[124:125], s[88:89], v121, s4, v[124:125]
	v_mov_b32_e32 v123, v124
	v_lshl_add_u64 v[122:123], v[122:123], 2, v[14:15]
	global_load_dwordx4 v[72:75], v[122:123], off nt
	v_add_u32_e32 v120, s80, v9
	v_ashrrev_i32_e32 v121, 31, v120
	v_mad_u64_u32 v[122:123], s[88:89], v120, s4, 0
	v_mov_b32_e32 v124, v123
	v_mov_b32_e32 v125, v115
	v_mad_u64_u32 v[124:125], s[88:89], v121, s4, v[124:125]
	v_mov_b32_e32 v123, v124
	v_lshl_add_u64 v[122:123], v[122:123], 2, v[14:15]
	global_load_dwordx4 v[76:79], v[122:123], off nt
	v_add_u32_e32 v120, s80, v18
	v_ashrrev_i32_e32 v121, 31, v120
	v_mad_u64_u32 v[122:123], s[88:89], v120, s4, 0
	v_mov_b32_e32 v124, v123
	v_mov_b32_e32 v125, v115
	v_mad_u64_u32 v[124:125], s[88:89], v121, s4, v[124:125]
	v_mov_b32_e32 v123, v124
	v_lshl_add_u64 v[122:123], v[122:123], 2, v[14:15]
	global_load_dwordx4 v[80:83], v[122:123], off nt
	v_add_u32_e32 v120, s80, v19
	v_ashrrev_i32_e32 v121, 31, v120
	v_mad_u64_u32 v[122:123], s[88:89], v120, s4, 0
	v_mov_b32_e32 v124, v123
	v_mov_b32_e32 v125, v115
	v_mad_u64_u32 v[124:125], s[88:89], v121, s4, v[124:125]
	v_mov_b32_e32 v123, v124
	v_lshl_add_u64 v[122:123], v[122:123], 2, v[14:15]
	global_load_dwordx4 v[84:87], v[122:123], off nt
	v_add_u32_e32 v120, s80, v20
	v_ashrrev_i32_e32 v121, 31, v120
	v_mad_u64_u32 v[122:123], s[88:89], v120, s4, 0
	v_mov_b32_e32 v124, v123
	v_mov_b32_e32 v125, v115
	v_mad_u64_u32 v[124:125], s[88:89], v121, s4, v[124:125]
	v_mov_b32_e32 v123, v124
	v_lshl_add_u64 v[122:123], v[122:123], 2, v[14:15]
	global_load_dwordx4 v[88:91], v[122:123], off nt
	v_add_u32_e32 v120, s80, v21
	v_ashrrev_i32_e32 v121, 31, v120
	v_mad_u64_u32 v[122:123], s[88:89], v120, s4, 0
	v_mov_b32_e32 v124, v123
	v_mov_b32_e32 v125, v115
	v_mad_u64_u32 v[124:125], s[88:89], v121, s4, v[124:125]
	v_mov_b32_e32 v123, v124
	v_lshl_add_u64 v[122:123], v[122:123], 2, v[14:15]
	global_load_dwordx4 v[92:95], v[122:123], off nt
	v_add_u32_e32 v120, s80, v22
	v_ashrrev_i32_e32 v121, 31, v120
	v_mad_u64_u32 v[122:123], s[88:89], v120, s4, 0
	v_mov_b32_e32 v124, v123
	v_mov_b32_e32 v125, v115
	v_mad_u64_u32 v[124:125], s[88:89], v121, s4, v[124:125]
	v_mov_b32_e32 v123, v124
	v_lshl_add_u64 v[122:123], v[122:123], 2, v[14:15]
	global_load_dwordx4 v[96:99], v[122:123], off nt
.Lcvt_skipA:
	s_or_b64 exec, exec, s[40:41]
	s_cmp_eq_u64 s[84:85], 0
	s_cbranch_scc1 .Lcvt_skipK
	v_add_u32_e32 v120, s80, v37
	v_ashrrev_i32_e32 v121, 31, v120
	v_lshl_add_u64 v[122:123], v[120:121], 2, s[84:85]
	global_load_dword v100, v[122:123], off
	v_add_u32_e32 v120, s80, v7
	v_ashrrev_i32_e32 v121, 31, v120
	v_lshl_add_u64 v[122:123], v[120:121], 2, s[84:85]
	global_load_dword v101, v[122:123], off
	v_add_u32_e32 v120, s80, v9
	v_ashrrev_i32_e32 v121, 31, v120
	v_lshl_add_u64 v[122:123], v[120:121], 2, s[84:85]
	global_load_dword v102, v[122:123], off
	v_add_u32_e32 v120, s80, v18
	v_ashrrev_i32_e32 v121, 31, v120
	v_lshl_add_u64 v[122:123], v[120:121], 2, s[84:85]
	global_load_dword v103, v[122:123], off
	v_add_u32_e32 v120, s80, v19
	v_ashrrev_i32_e32 v121, 31, v120
	v_lshl_add_u64 v[122:123], v[120:121], 2, s[84:85]
	global_load_dword v104, v[122:123], off
	v_add_u32_e32 v120, s80, v20
	v_ashrrev_i32_e32 v121, 31, v120
	v_lshl_add_u64 v[122:123], v[120:121], 2, s[84:85]
	global_load_dword v105, v[122:123], off
	v_add_u32_e32 v120, s80, v21
	v_ashrrev_i32_e32 v121, 31, v120
	v_lshl_add_u64 v[122:123], v[120:121], 2, s[84:85]
	global_load_dword v106, v[122:123], off
	v_add_u32_e32 v120, s80, v22
	v_ashrrev_i32_e32 v121, 31, v120
	v_lshl_add_u64 v[122:123], v[120:121], 2, s[84:85]
	global_load_dword v107, v[122:123], off
.Lcvt_skipK:
	s_waitcnt vmcnt(0)
	s_and_saveexec_b64 s[40:41], s[38:39]
	s_cbranch_execz .LBB0_90
	v_mov_b32_e32 v2, v68
	v_mov_b32_e32 v3, v69
	v_mov_b32_e32 v4, v70
	v_mov_b32_e32 v5, v71
.LBB0_90:
	s_or_b64 exec, exec, s[40:41]
	s_cmp_lg_u64 s[84:85], 0
	s_cselect_b64 vcc, -1, 0
	s_cmp_eq_u64 s[84:85], 0
	s_cbranch_scc1 .LBB0_92
	v_mov_b32_e32 v16, v100
	s_waitcnt vmcnt(0)
	v_pk_mul_f32 v[4:5], v[4:5], v[16:17] op_sel_hi:[1,0]
	v_pk_mul_f32 v[2:3], v[2:3], v[16:17] op_sel_hi:[1,0]
.LBB0_92:
	v_mov_b32_e32 v114, v115
	s_waitcnt vmcnt(0)
	ds_write2_b32 v28, v2, v3 offset1:1
	ds_write2_b32 v28, v4, v5 offset0:2 offset1:3
	v_mov_b32_e32 v116, v115
	v_mov_b32_e32 v117, v115
	v_add_u32_e32 v16, s80, v7
	v_mov_b64_e32 v[2:3], v[114:115]
	v_ashrrev_i32_e32 v17, 31, v16
	v_mov_b64_e32 v[4:5], v[116:117]
	s_and_saveexec_b64 s[40:41], s[38:39]
	s_cbranch_execz .LBB0_94
	v_mov_b32_e32 v2, v72
	v_mov_b32_e32 v3, v73
	v_mov_b32_e32 v4, v74
	v_mov_b32_e32 v5, v75
.LBB0_94:
	s_or_b64 exec, exec, s[40:41]
	v_cndmask_b32_e64 v40, 0, 1, vcc
	v_cmp_ne_u32_e64 s[40:41], 1, v40
	s_andn2_b64 vcc, exec, vcc
	s_cbranch_vccnz .LBB0_96
	v_mov_b32_e32 v16, v101
	s_waitcnt vmcnt(0)
	v_pk_mul_f32 v[4:5], v[4:5], v[16:17] op_sel_hi:[1,0]
	v_pk_mul_f32 v[2:3], v[2:3], v[16:17] op_sel_hi:[1,0]
.LBB0_96:
	v_mov_b32_e32 v114, v115
	s_waitcnt vmcnt(0)
	ds_write2_b32 v29, v2, v3 offset1:1
	ds_write2_b32 v29, v4, v5 offset0:2 offset1:3
	v_mov_b32_e32 v116, v115
	v_mov_b32_e32 v117, v115
	v_add_u32_e32 v16, s80, v9
	v_mov_b64_e32 v[2:3], v[114:115]
	v_ashrrev_i32_e32 v17, 31, v16
	v_mov_b64_e32 v[4:5], v[116:117]
	s_and_saveexec_b64 vcc, s[38:39]
	s_cbranch_execz .LBB0_98
	v_mov_b32_e32 v2, v76
	v_mov_b32_e32 v3, v77
	v_mov_b32_e32 v4, v78
	v_mov_b32_e32 v5, v79
.LBB0_98:
	s_or_b64 exec, exec, vcc
	s_and_b64 vcc, exec, s[40:41]
	s_cbranch_vccnz .LBB0_100
	v_mov_b32_e32 v16, v102
	s_waitcnt vmcnt(0)
	v_pk_mul_f32 v[4:5], v[4:5], v[16:17] op_sel_hi:[1,0]
	v_pk_mul_f32 v[2:3], v[2:3], v[16:17] op_sel_hi:[1,0]
.LBB0_100:
	v_mov_b32_e32 v114, v115
	s_waitcnt vmcnt(0)
	ds_write2_b32 v30, v2, v3 offset1:1
	ds_write2_b32 v30, v4, v5 offset0:2 offset1:3
	v_mov_b32_e32 v116, v115
	v_mov_b32_e32 v117, v115
	v_add_u32_e32 v16, s80, v18
	v_mov_b64_e32 v[2:3], v[114:115]
	v_ashrrev_i32_e32 v17, 31, v16
	v_mov_b64_e32 v[4:5], v[116:117]
	s_and_saveexec_b64 vcc, s[38:39]
	s_cbranch_execz .LBB0_102
	v_mov_b32_e32 v2, v80
	v_mov_b32_e32 v3, v81
	v_mov_b32_e32 v4, v82
	v_mov_b32_e32 v5, v83
.LBB0_102:
	s_or_b64 exec, exec, vcc
	s_and_b64 vcc, exec, s[40:41]
	s_cbranch_vccnz .LBB0_104
	v_mov_b32_e32 v16, v103
	s_waitcnt vmcnt(0)
	v_pk_mul_f32 v[4:5], v[4:5], v[16:17] op_sel_hi:[1,0]
	v_pk_mul_f32 v[2:3], v[2:3], v[16:17] op_sel_hi:[1,0]
.LBB0_104:
	v_mov_b32_e32 v114, v115
	s_waitcnt vmcnt(0)
	ds_write2_b32 v31, v2, v3 offset1:1
	ds_write2_b32 v31, v4, v5 offset0:2 offset1:3
	v_mov_b32_e32 v116, v115
	v_mov_b32_e32 v117, v115
	v_add_u32_e32 v16, s80, v19
	v_mov_b64_e32 v[2:3], v[114:115]
	v_ashrrev_i32_e32 v17, 31, v16
	v_mov_b64_e32 v[4:5], v[116:117]
	s_and_saveexec_b64 vcc, s[38:39]
	s_cbranch_execz .LBB0_106
	v_mov_b32_e32 v2, v84
	v_mov_b32_e32 v3, v85
	v_mov_b32_e32 v4, v86
	v_mov_b32_e32 v5, v87
.LBB0_106:
	s_or_b64 exec, exec, vcc
	s_and_b64 vcc, exec, s[40:41]
	s_cbranch_vccnz .LBB0_108
	v_mov_b32_e32 v16, v104
	s_waitcnt vmcnt(0)
	v_pk_mul_f32 v[4:5], v[4:5], v[16:17] op_sel_hi:[1,0]
	v_pk_mul_f32 v[2:3], v[2:3], v[16:17] op_sel_hi:[1,0]
.LBB0_108:
	v_mov_b32_e32 v114, v115
	s_waitcnt vmcnt(0)
	ds_write2_b32 v32, v2, v3 offset1:1
	ds_write2_b32 v32, v4, v5 offset0:2 offset1:3
	v_mov_b32_e32 v116, v115
	v_mov_b32_e32 v117, v115
	v_add_u32_e32 v16, s80, v20
	v_mov_b64_e32 v[2:3], v[114:115]
	v_ashrrev_i32_e32 v17, 31, v16
	v_mov_b64_e32 v[4:5], v[116:117]
	s_and_saveexec_b64 vcc, s[38:39]
	s_cbranch_execz .LBB0_110
	v_mov_b32_e32 v2, v88
	v_mov_b32_e32 v3, v89
	v_mov_b32_e32 v4, v90
	v_mov_b32_e32 v5, v91
.LBB0_110:
	s_or_b64 exec, exec, vcc
	s_and_b64 vcc, exec, s[40:41]
	s_cbranch_vccnz .LBB0_112
	v_mov_b32_e32 v16, v105
	s_waitcnt vmcnt(0)
	v_pk_mul_f32 v[4:5], v[4:5], v[16:17] op_sel_hi:[1,0]
	v_pk_mul_f32 v[2:3], v[2:3], v[16:17] op_sel_hi:[1,0]
.LBB0_112:
	v_mov_b32_e32 v114, v115
	s_waitcnt vmcnt(0)
	ds_write2_b32 v33, v2, v3 offset1:1
	ds_write2_b32 v33, v4, v5 offset0:2 offset1:3
	v_mov_b32_e32 v116, v115
	v_mov_b32_e32 v117, v115
	v_add_u32_e32 v16, s80, v21
	v_mov_b64_e32 v[2:3], v[114:115]
	v_ashrrev_i32_e32 v17, 31, v16
	v_mov_b64_e32 v[4:5], v[116:117]
	s_and_saveexec_b64 vcc, s[38:39]
	s_cbranch_execz .LBB0_114
	v_mov_b32_e32 v2, v92
	v_mov_b32_e32 v3, v93
	v_mov_b32_e32 v4, v94
	v_mov_b32_e32 v5, v95
.LBB0_114:
	s_or_b64 exec, exec, vcc
	s_and_b64 vcc, exec, s[40:41]
	s_cbranch_vccnz .LBB0_116
	v_mov_b32_e32 v16, v106
	s_waitcnt vmcnt(0)
	v_pk_mul_f32 v[4:5], v[4:5], v[16:17] op_sel_hi:[1,0]
	v_pk_mul_f32 v[2:3], v[2:3], v[16:17] op_sel_hi:[1,0]
.LBB0_116:
	v_mov_b32_e32 v114, v115
	s_waitcnt vmcnt(0)
	ds_write2_b32 v38, v2, v3 offset1:1
	ds_write2_b32 v38, v4, v5 offset0:2 offset1:3
	v_mov_b32_e32 v116, v115
	v_mov_b32_e32 v117, v115
	v_add_u32_e32 v16, s80, v22
	v_mov_b64_e32 v[2:3], v[114:115]
	v_ashrrev_i32_e32 v17, 31, v16
	v_mov_b64_e32 v[4:5], v[116:117]
	s_and_saveexec_b64 vcc, s[38:39]
	s_cbranch_execz .LBB0_118
	v_mov_b32_e32 v2, v96
	v_mov_b32_e32 v3, v97
	v_mov_b32_e32 v4, v98
	v_mov_b32_e32 v5, v99
.LBB0_118:
	s_or_b64 exec, exec, vcc
	s_and_b64 vcc, exec, s[40:41]
	s_cbranch_vccnz .LBB0_120
	v_mov_b32_e32 v14, v107
	s_waitcnt vmcnt(0)
	v_pk_mul_f32 v[4:5], v[4:5], v[14:15] op_sel_hi:[1,0]
	v_pk_mul_f32 v[2:3], v[2:3], v[14:15] op_sel_hi:[1,0]
